# DFT-matrix copy at the start of each Fourier stage: the four row-block loads issued together then the four LDS writes behind counted waits (was four serialized load-wait-write rounds)
# speedup vs baseline: 1.0058x; 1.0058x over previous
.LBB0_326:
	s_or_b64 exec, exec, s[10:11]
	v_mov_b32_e32 v122, v221
	s_movk_i32 s0, 0x800
	s_waitcnt vmcnt(0)
	v_readfirstlane_b32 s15, v122
	v_cmp_gt_i32_e32 vcc, s0, v122
	v_lshlrev_b32_e32 v32, 3, v122
	s_barrier
	s_and_saveexec_b64 s[0:1], vcc
	s_movk_i32 s2, 0x110
	s_movk_i32 s4, 0x5ff
	s_cbranch_execz .LBB0_329
	v_ashrrev_i32_e32 v6, 4, v122
	v_lshlrev_b32_e32 v3, 4, v122
	v_lshlrev_b32_e32 v2, 7, v6
	v_and_b32_e32 v208, 0xf0, v3
	v_ashrrev_i32_e32 v3, 31, v2
	v_lshl_add_u64 v[2:3], v[2:3], 1, s[64:65]
	v_lshl_add_u64 v[20:21], v[2:3], 0, v[208:209]
	s_mov_b32 s10, 0x2000
	s_mov_b32 s11, 0
	v_lshl_add_u64 v[22:23], v[20:21], 0, s[10:11]
	v_lshl_add_u64 v[24:25], v[22:23], 0, s[10:11]
	v_lshl_add_u64 v[26:27], v[24:25], 0, s[10:11]
	global_load_dwordx4 v[2:5], v[20:21], off
	global_load_dwordx4 v[8:11], v[22:23], off
	global_load_dwordx4 v[12:15], v[24:25], off
	global_load_dwordx4 v[16:19], v[26:27], off
	v_mul_lo_u32 v6, v6, s2
	v_add3_u32 v6, 0, v6, v208
	s_waitcnt vmcnt(3)
	ds_write_b128 v6, v[2:5]
	s_waitcnt vmcnt(2)
	ds_write_b128 v6, v[8:11] offset:8704
	s_waitcnt vmcnt(1)
	ds_write_b128 v6, v[12:15] offset:17408
	s_waitcnt vmcnt(0)
	ds_write_b128 v6, v[16:19] offset:26112

.LBB0_382:
	v_mov_b32_e32 v32, v221
	s_movk_i32 s0, 0x800
	s_barrier
	s_nop 0
	v_readfirstlane_b32 s16, v32
	v_cmp_gt_i32_e32 vcc, s0, v32
	v_lshlrev_b32_e32 v33, 3, v32
	s_barrier
	s_and_saveexec_b64 s[0:1], vcc
	v_readlane_b32 s4, v253, 63
	v_readlane_b32 s5, v254, 0
	s_movk_i32 s6, 0x110
	s_movk_i32 s17, 0x5ff
	s_cbranch_execz .LBB0_385
	v_ashrrev_i32_e32 v6, 4, v32
	v_lshlrev_b32_e32 v3, 4, v32
	v_lshlrev_b32_e32 v2, 7, v6
	v_and_b32_e32 v208, 0xf0, v3
	v_ashrrev_i32_e32 v3, 31, v2
	v_lshl_add_u64 v[2:3], v[2:3], 1, s[4:5]
	v_lshl_add_u64 v[20:21], v[2:3], 0, v[208:209]
	s_mov_b32 s10, 0x2000
	s_mov_b32 s11, 0
	v_lshl_add_u64 v[22:23], v[20:21], 0, s[10:11]
	v_lshl_add_u64 v[24:25], v[22:23], 0, s[10:11]
	v_lshl_add_u64 v[26:27], v[24:25], 0, s[10:11]
	global_load_dwordx4 v[2:5], v[20:21], off
	global_load_dwordx4 v[8:11], v[22:23], off
	global_load_dwordx4 v[12:15], v[24:25], off
	global_load_dwordx4 v[16:19], v[26:27], off
	v_mul_lo_u32 v6, v6, s6
	v_add3_u32 v6, 0, v6, v208
	s_waitcnt vmcnt(3)
	ds_write_b128 v6, v[2:5]
	s_waitcnt vmcnt(2)
	ds_write_b128 v6, v[8:11] offset:8704
	s_waitcnt vmcnt(1)
	ds_write_b128 v6, v[12:15] offset:17408
	s_waitcnt vmcnt(0)
	ds_write_b128 v6, v[16:19] offset:26112
